# lru_tile conv: all x-row/weight loads issued up front (4 serialized tap round-trips -> 1)
# speedup vs baseline: 1.0096x; 1.0025x over previous
.LBB0_643:
	s_andn2_b64 vcc, exec, s[10:11]
	s_cbranch_vccnz .LBB0_655
	s_add_i32 s4, s91, 0xfe40
	s_and_b32 s5, s4, 0xffff
	s_mul_i32 s5, s5, 0xaaab
	s_lshr_b32 s26, s5, 18
	s_mul_i32 s5, s26, 6
	v_readlane_b32 s18, v250, 57
	v_mov_b32_e32 v39, v203
	s_sub_i32 s4, s4, s5
	s_mov_b32 s5, 64
	v_readlane_b32 s19, v250, 58
	s_load_dwordx2 s[10:11], s[18:19], s5 offset:0x0
	s_and_b32 s4, s4, 0xffff
	s_lshl_b64 s[12:13], s[16:17], 2
	v_lshlrev_b32_e32 v0, 4, v39
	v_and_b32_e32 v38, 0x70, v0
	s_waitcnt lgkmcnt(0)
	s_add_u32 s5, s10, s12
	s_addc_u32 s11, s11, s13
	s_lshl_b32 s12, s4, 9
	s_add_u32 s10, s5, s12
	s_addc_u32 s11, s11, 0
	v_lshlrev_b32_e32 v0, 2, v38
	s_mov_b32 s5, 56
	global_load_dwordx4 v[2:5], v0, s[10:11] offset:48
	global_load_dwordx4 v[6:9], v0, s[10:11] offset:32
	global_load_dwordx4 v[10:13], v0, s[10:11] offset:16
	global_load_dwordx4 v[14:17], v0, s[10:11]
	s_load_dwordx2 s[10:11], s[18:19], s5 offset:0x0
	s_mul_i32 s13, s52, 0x3000
	v_ashrrev_i32_e32 v22, 3, v39
	v_lshl_add_u32 v40, s26, 6, v22
	v_lshlrev_b32_e32 v34, 1, v38
	s_waitcnt lgkmcnt(0)
	s_add_u32 s10, s10, s13
	s_addc_u32 s11, s11, 0
	s_add_u32 s10, s10, s12
	s_addc_u32 s11, s11, 0
	v_lshl_add_u64 v[18:19], s[10:11], 0, v[0:1]
	s_lshl_b32 s10, s4, 8
	s_add_u32 s10, s14, s10
	s_addc_u32 s11, s15, 0
	v_mov_b32_e32 v35, v1
	v_readfirstlane_b32 s5, v39
	v_lshl_add_u64 v[20:21], s[10:11], 0, v[34:35]
	v_add_u32_e32 v0, -3, v40
	v_max_i32_e32 v0, 0, v0
	v_mad_u64_u32 v[28:29], s[12:13], v0, s63, v[20:21]
	global_load_dwordx4 v[70:73], v[28:29], off offset:16
	global_load_dwordx4 v[74:77], v[28:29], off
	v_add_u32_e32 v0, -2, v40
	v_max_i32_e32 v0, 0, v0
	v_mad_u64_u32 v[28:29], s[12:13], v0, s63, v[20:21]
	global_load_dwordx4 v[78:81], v[28:29], off offset:16
	global_load_dwordx4 v[82:85], v[28:29], off
	v_add_u32_e32 v0, -1, v40
	v_max_i32_e32 v0, 0, v0
	v_mad_u64_u32 v[28:29], s[12:13], v0, s63, v[20:21]
	global_load_dwordx4 v[86:89], v[28:29], off offset:16
	global_load_dwordx4 v[90:93], v[28:29], off
	v_mad_u64_u32 v[28:29], s[12:13], v40, s63, v[20:21]
	global_load_dwordx4 v[94:97], v[28:29], off offset:16
	global_load_dwordx4 v[98:101], v[28:29], off
	s_mov_b64 s[12:13], 0x1800
	v_lshl_add_u64 v[30:31], v[18:19], 0, s[12:13]
	global_load_dwordx4 v[54:57], v[18:19], off
	global_load_dwordx4 v[50:53], v[18:19], off offset:16
	global_load_dwordx4 v[46:49], v[18:19], off offset:32
	global_load_dwordx4 v[42:45], v[18:19], off offset:48
	global_load_dwordx4 v[102:105], v[18:19], off offset:3072
	global_load_dwordx4 v[106:109], v[18:19], off offset:3088
	global_load_dwordx4 v[110:113], v[18:19], off offset:3104
	global_load_dwordx4 v[114:117], v[18:19], off offset:3120
	global_load_dwordx4 v[118:121], v[30:31], off
	global_load_dwordx4 v[122:125], v[30:31], off offset:16
	global_load_dwordx4 v[126:129], v[30:31], off offset:32
	global_load_dwordx4 v[130:133], v[30:31], off offset:48
	global_load_dwordx4 v[58:61], v[30:31], off offset:3072
	global_load_dwordx4 v[62:65], v[30:31], off offset:3088
	global_load_dwordx4 v[66:69], v[30:31], off offset:3104
	global_load_dwordx4 v[134:137], v[30:31], off offset:3120
	v_cmp_lt_i32_e32 vcc, 2, v40
	s_and_saveexec_b64 s[10:11], vcc
	s_waitcnt vmcnt(12)
	v_lshlrev_b32_e32 v32, 16, v74
	v_and_b32_e32 v33, 0xffff0000, v74
	v_pk_fma_f32 v[14:15], v[54:55], v[32:33], v[14:15]
	v_lshlrev_b32_e32 v28, 16, v75
	v_and_b32_e32 v29, 0xffff0000, v75
	v_pk_fma_f32 v[16:17], v[56:57], v[28:29], v[16:17]
	v_lshlrev_b32_e32 v24, 16, v76
	v_and_b32_e32 v25, 0xffff0000, v76
	v_pk_fma_f32 v[10:11], v[50:51], v[24:25], v[10:11]
	v_lshlrev_b32_e32 v26, 16, v77
	v_and_b32_e32 v27, 0xffff0000, v77
	v_pk_fma_f32 v[12:13], v[52:53], v[26:27], v[12:13]
	v_lshlrev_b32_e32 v32, 16, v70
	v_and_b32_e32 v33, 0xffff0000, v70
	v_pk_fma_f32 v[6:7], v[46:47], v[32:33], v[6:7]
	v_lshlrev_b32_e32 v28, 16, v71
	v_and_b32_e32 v29, 0xffff0000, v71
	v_pk_fma_f32 v[8:9], v[48:49], v[28:29], v[8:9]
	v_lshlrev_b32_e32 v24, 16, v72
	v_and_b32_e32 v25, 0xffff0000, v72
	v_pk_fma_f32 v[2:3], v[42:43], v[24:25], v[2:3]
	v_lshlrev_b32_e32 v26, 16, v73
	v_and_b32_e32 v27, 0xffff0000, v73
	v_pk_fma_f32 v[4:5], v[44:45], v[26:27], v[4:5]
	s_or_b64 exec, exec, s[10:11]
	v_cmp_lt_i32_e32 vcc, 1, v40
	s_and_saveexec_b64 s[10:11], vcc
	s_waitcnt vmcnt(8)
	v_lshlrev_b32_e32 v32, 16, v82
	v_and_b32_e32 v33, 0xffff0000, v82
	v_pk_fma_f32 v[14:15], v[102:103], v[32:33], v[14:15]
	v_lshlrev_b32_e32 v28, 16, v83
	v_and_b32_e32 v29, 0xffff0000, v83
	v_pk_fma_f32 v[16:17], v[104:105], v[28:29], v[16:17]
	v_lshlrev_b32_e32 v24, 16, v84
	v_and_b32_e32 v25, 0xffff0000, v84
	v_pk_fma_f32 v[10:11], v[106:107], v[24:25], v[10:11]
	v_lshlrev_b32_e32 v26, 16, v85
	v_and_b32_e32 v27, 0xffff0000, v85
	v_pk_fma_f32 v[12:13], v[108:109], v[26:27], v[12:13]
	v_lshlrev_b32_e32 v32, 16, v78
	v_and_b32_e32 v33, 0xffff0000, v78
	v_pk_fma_f32 v[6:7], v[110:111], v[32:33], v[6:7]
	v_lshlrev_b32_e32 v28, 16, v79
	v_and_b32_e32 v29, 0xffff0000, v79
	v_pk_fma_f32 v[8:9], v[112:113], v[28:29], v[8:9]
	v_lshlrev_b32_e32 v24, 16, v80
	v_and_b32_e32 v25, 0xffff0000, v80
	v_pk_fma_f32 v[2:3], v[114:115], v[24:25], v[2:3]
	v_lshlrev_b32_e32 v26, 16, v81
	v_and_b32_e32 v27, 0xffff0000, v81
	v_pk_fma_f32 v[4:5], v[116:117], v[26:27], v[4:5]
	s_or_b64 exec, exec, s[10:11]
	v_cmp_lt_i32_e32 vcc, 0, v40
	s_and_saveexec_b64 s[10:11], vcc
	s_waitcnt vmcnt(4)
	v_lshlrev_b32_e32 v32, 16, v90
	v_and_b32_e32 v33, 0xffff0000, v90
	v_pk_fma_f32 v[14:15], v[118:119], v[32:33], v[14:15]
	v_lshlrev_b32_e32 v28, 16, v91
	v_and_b32_e32 v29, 0xffff0000, v91
	v_pk_fma_f32 v[16:17], v[120:121], v[28:29], v[16:17]
	v_lshlrev_b32_e32 v24, 16, v92
	v_and_b32_e32 v25, 0xffff0000, v92
	v_pk_fma_f32 v[10:11], v[122:123], v[24:25], v[10:11]
	v_lshlrev_b32_e32 v26, 16, v93
	v_and_b32_e32 v27, 0xffff0000, v93
	v_pk_fma_f32 v[12:13], v[124:125], v[26:27], v[12:13]
	v_lshlrev_b32_e32 v32, 16, v86
	v_and_b32_e32 v33, 0xffff0000, v86
	v_pk_fma_f32 v[6:7], v[126:127], v[32:33], v[6:7]
	v_lshlrev_b32_e32 v28, 16, v87
	v_and_b32_e32 v29, 0xffff0000, v87
	v_pk_fma_f32 v[8:9], v[128:129], v[28:29], v[8:9]
	v_lshlrev_b32_e32 v24, 16, v88
	v_and_b32_e32 v25, 0xffff0000, v88
	v_pk_fma_f32 v[2:3], v[130:131], v[24:25], v[2:3]
	v_lshlrev_b32_e32 v26, 16, v89
	v_and_b32_e32 v27, 0xffff0000, v89
	v_pk_fma_f32 v[4:5], v[132:133], v[26:27], v[4:5]
	s_or_b64 exec, exec, s[10:11]
	s_lshl_b32 s68, s4, 7
	v_cmp_lt_i32_e32 vcc, -1, v40
	s_and_saveexec_b64 s[10:11], vcc
	s_waitcnt vmcnt(0)
	v_lshlrev_b32_e32 v32, 16, v98
	v_and_b32_e32 v33, 0xffff0000, v98
	v_pk_fma_f32 v[14:15], v[58:59], v[32:33], v[14:15]
	v_lshlrev_b32_e32 v28, 16, v99
	v_and_b32_e32 v29, 0xffff0000, v99
	v_pk_fma_f32 v[16:17], v[60:61], v[28:29], v[16:17]
	v_lshlrev_b32_e32 v24, 16, v100
	v_and_b32_e32 v25, 0xffff0000, v100
	v_pk_fma_f32 v[10:11], v[62:63], v[24:25], v[10:11]
	v_lshlrev_b32_e32 v26, 16, v101
	v_and_b32_e32 v27, 0xffff0000, v101
	v_pk_fma_f32 v[12:13], v[64:65], v[26:27], v[12:13]
	v_lshlrev_b32_e32 v32, 16, v94
	v_and_b32_e32 v33, 0xffff0000, v94
	v_pk_fma_f32 v[6:7], v[66:67], v[32:33], v[6:7]
	v_lshlrev_b32_e32 v28, 16, v95
	v_and_b32_e32 v29, 0xffff0000, v95
	v_pk_fma_f32 v[8:9], v[68:69], v[28:29], v[8:9]
	v_lshlrev_b32_e32 v24, 16, v96
	v_and_b32_e32 v25, 0xffff0000, v96
	v_pk_fma_f32 v[2:3], v[134:135], v[24:25], v[2:3]
	v_lshlrev_b32_e32 v26, 16, v97
	v_and_b32_e32 v27, 0xffff0000, v97
	v_pk_fma_f32 v[4:5], v[136:137], v[26:27], v[4:5]
	s_or_b64 exec, exec, s[10:11]

.LBB0_798:
	s_andn2_b64 vcc, exec, s[34:35]
	s_cbranch_vccnz .LBB0_550
	s_add_u32 s5, s89, s30
	s_addc_u32 s10, s90, s31
	s_add_i32 s11, s26, s28
	s_lshl_b32 s4, s4, 5
	v_or_b32_e32 v6, s11, v26
	s_add_u32 s4, s5, s4
	s_addc_u32 s5, s10, 0
	v_lshlrev_b32_e32 v0, 1, v29
	v_ashrrev_i32_e32 v7, 31, v6
	v_lshl_add_u64 v[8:9], s[4:5], 0, v[0:1]
	v_lshlrev_b64 v[10:11], 7, v[6:7]
	v_cvt_pk_bf16_f32 v0, v2, s0
	v_lshl_add_u64 v[10:11], v[8:9], 0, v[10:11]
	v_or_b32_e32 v2, 1, v6
	global_store_short v[10:11], v0, off
	v_cvt_pk_bf16_f32 v0, v3, s0
	v_ashrrev_i32_e32 v3, 31, v2
	v_lshlrev_b64 v[2:3], 7, v[2:3]
	v_lshl_add_u64 v[2:3], v[8:9], 0, v[2:3]
	global_store_short v[2:3], v0, off
	v_or_b32_e32 v2, 2, v6
	v_ashrrev_i32_e32 v3, 31, v2
	v_lshlrev_b64 v[2:3], 7, v[2:3]
	v_cvt_pk_bf16_f32 v0, v4, s0
	v_lshl_add_u64 v[2:3], v[8:9], 0, v[2:3]
	global_store_short v[2:3], v0, off
	v_or_b32_e32 v2, 3, v6
	v_ashrrev_i32_e32 v3, 31, v2
	v_lshlrev_b64 v[2:3], 7, v[2:3]
	v_cvt_pk_bf16_f32 v0, v5, s0
	v_lshl_add_u64 v[2:3], v[8:9], 0, v[2:3]
	global_store_short v[2:3], v0, off
	s_branch .LBB0_550
.LBB0_802:
	s_getreg_b32 s4, hwreg(HW_REG_XCC_ID, 0, 4)
	s_waitcnt vmcnt(0)
	s_waitcnt lgkmcnt(0)
	s_barrier
	s_mov_b64 s[6:7], exec
	v_readlane_b32 s10, v250, 5
	v_readlane_b32 s11, v250, 6
	s_and_b64 s[10:11], s[6:7], s[10:11]
	v_readlane_b32 s53, v250, 59
	s_mov_b64 exec, s[10:11]
	s_cbranch_execz .LBB0_854
	v_readlane_b32 s5, v250, 38
	s_waitcnt vmcnt(0) expcnt(0) lgkmcnt(0)
	s_and_b32 s4, s4, 15
	v_mov_b32_e32 v0, s5
	ds_read_b32 v3, v0
	v_readlane_b32 s5, v250, 39
	s_waitcnt lgkmcnt(0)
	v_cmp_ne_u32_e32 vcc, 0, v3
	v_mov_b32_e32 v0, s5
	ds_read_b32 v2, v0
	s_cbranch_vccnz .LBB0_818
	s_add_u32 s10, s66, 0x104600
	s_addc_u32 s11, s67, 0
	s_add_u32 s12, s66, 0x104800
	s_addc_u32 s13, s67, 0
	s_add_u32 s14, s66, 0x104900
	s_addc_u32 s15, s67, 0
	s_add_u32 s16, s66, 0x104a00
	s_addc_u32 s17, s67, 0
	s_add_u32 s18, s66, 0x104b00
	s_addc_u32 s19, s67, 0
	s_add_u32 s20, s66, 0x104c00
	s_addc_u32 s21, s67, 0
	s_add_u32 s22, s66, 0x104d00
	s_addc_u32 s23, s67, 0
	s_add_u32 s24, s66, 0x104e00
	s_addc_u32 s25, s67, 0
	s_add_u32 s26, s66, 0x104f00
	s_addc_u32 s27, s67, 0
	s_add_u32 s28, s66, 0x105000
	s_addc_u32 s29, s67, 0
	s_add_u32 s30, s66, 0x105100
	s_addc_u32 s31, s67, 0
	s_add_u32 s34, s66, 0x105200
	s_addc_u32 s35, s67, 0
	s_add_u32 s36, s66, 0x105300
	s_addc_u32 s37, s67, 0
	s_add_u32 s38, s66, 0x105400
	s_addc_u32 s39, s67, 0
	s_add_u32 s40, s66, 0x105500
	s_addc_u32 s41, s67, 0
	s_add_u32 s42, s66, 0x105600
	s_addc_u32 s43, s67, 0
	s_add_u32 s44, s66, 0x105700
	s_addc_u32 s45, s67, 0
	s_mov_b32 s5, 1
	s_branch .LBB0_806
